# attention unit queue: next-unit atomic pop issued before the 8 output stores and consumed with vmcnt(8) so the store acks are off the per-wave critical path (on top of k36)
# speedup vs baseline: 1.0022x; 1.0022x over previous
.LBB0_1492:
	v_readlane_b32 s2, v255, 3
	v_readlane_b32 s3, v255, 4
	s_mov_b64 s[8:9], exec
	s_mov_b64 exec, s[6:7]
	v_mov_b32_e32 v234, 1
	s_nop 3
	global_atomic_add v234, v1, v234, s[2:3] sc0
	s_mov_b64 exec, s[8:9]
	v_lshlrev_b32_e32 v36, 2, v189
	v_ashrrev_i32_e32 v37, 31, v36
	v_lshl_add_u64 v[34:35], v[36:37], 1, v[34:35]
	v_cvt_pk_bf16_f32 v4, v4, v5
	v_cvt_pk_bf16_f32 v5, v8, v9
	v_cvt_pk_bf16_f32 v2, v2, v3
	v_cvt_pk_bf16_f32 v3, v6, v7
	global_store_dwordx2 v[34:35], v[4:5], off
	v_cvt_pk_bf16_f32 v4, v12, v13
	v_cvt_pk_bf16_f32 v5, v18, v19
	global_store_dwordx2 v[34:35], v[2:3], off offset:64
	v_cvt_pk_bf16_f32 v2, v10, v11
	v_cvt_pk_bf16_f32 v3, v14, v15
	global_store_dwordx2 v[34:35], v[4:5], off offset:16
	v_cvt_pk_bf16_f32 v4, v20, v21
	v_cvt_pk_bf16_f32 v5, v24, v25
	global_store_dwordx2 v[34:35], v[2:3], off offset:80
	v_cvt_pk_bf16_f32 v2, v16, v17
	v_cvt_pk_bf16_f32 v3, v22, v23
	global_store_dwordx2 v[34:35], v[4:5], off offset:32
	v_cvt_pk_bf16_f32 v4, v28, v29
	v_cvt_pk_bf16_f32 v5, v32, v33
	global_store_dwordx2 v[34:35], v[2:3], off offset:96
	v_cvt_pk_bf16_f32 v2, v26, v27
	v_cvt_pk_bf16_f32 v3, v30, v31
	s_mov_b64 s[0:1], 0
	global_store_dwordx2 v[34:35], v[4:5], off offset:48
	global_store_dwordx2 v[34:35], v[2:3], off offset:112
	s_mov_b64 s[34:35], 0x80
	s_mov_b64 s[4:5], s[6:7]
	s_waitcnt vmcnt(8)
	v_readfirstlane_b32 s40, v234
	s_branch .Lpop_done

.Lpop_done:
	s_cmpk_gt_u32 s40, 0x7ff
	s_mov_b64 s[0:1], -1
	s_cbranch_scc1 .LBB0_1493
	s_xor_b32 s40, s40, 0x400
	v_mov_b32_e32 v188, v240
	s_cmpk_gt_u32 s40, 0x3ff
	v_ashrrev_i32_e32 v196, 5, v188
	s_cbranch_scc0 .LBB0_1565
	s_not_b32 s0, s40
	s_bfe_u32 s42, s0, 0x60002
	v_ashrrev_i32_e32 v189, 5, v188
	s_and_b32 s43, s40, 3
	s_lshl_b32 s41, s42, 5
	s_waitcnt vmcnt(15)
	v_lshlrev_b32_e32 v146, 3, v189
	s_cmpk_gt_u32 s40, 0x5ff
	v_and_or_b32 v190, v188, 31, s41
	v_ashrrev_i32_e32 v147, 31, v146
	s_mov_b64 s[0:1], -1
	s_cbranch_scc0 .LBB0_1541
	s_add_i32 s0, s40, 0xfffffa00
	s_lshr_b32 s0, s0, 6
	s_and_b32 s0, s0, 0x3fffffc
	v_readlane_b32 s1, v255, 1
	s_add_i32 s0, s0, s1
	s_or_b32 s36, s0, s43
	s_lshl_b32 s0, s0, 9
	s_and_b32 s0, s0, 0x7800
	v_or_b32_e32 v184, s0, v190
	v_readlane_b32 s0, v255, 6
	v_lshlrev_b32_e32 v0, 9, v184
	v_readlane_b32 s1, v255, 7
	s_mov_b32 s19, s37
	v_readlane_b32 s2, v255, 10
	v_lshl_add_u64 v[2:3], s[0:1], 0, v[0:1]
	s_lshl_b32 s0, s36, 6
	s_and_b32 s0, s0, 0xc0
	s_lshl_b32 s18, s0, 1
	v_lshl_add_u64 v[2:3], v[2:3], 0, s[18:19]
	v_lshl_add_u64 v[2:3], v[146:147], 1, v[2:3]
	global_load_dwordx4 v[66:69], v[2:3], off
	global_load_dwordx4 v[70:73], v[2:3], off offset:32
	global_load_dwordx4 v[74:77], v[2:3], off offset:64
	global_load_dwordx4 v[78:81], v[2:3], off offset:96
	s_lshl_b64 s[0:1], s[36:37], 11
	s_add_u32 s0, s2, s0
	v_readlane_b32 s2, v255, 11
	s_addc_u32 s1, s2, s1
	s_cmp_lt_u32 s42, 8
	v_lshl_add_u64 v[2:3], v[146:147], 2, s[0:1]
	s_cselect_b64 s[0:1], -1, 0
	v_mov_b32_e32 v0, 0
	v_mov_b32_e32 v16, 0
	s_and_b64 vcc, exec, s[0:1]
	s_waitcnt vmcnt(3)
	v_lshlrev_b32_e32 v29, 16, v66
	v_lshlrev_b32_e32 v30, 16, v68
	v_and_b32_e32 v31, 0xffff0000, v66
	v_and_b32_e32 v32, 0xffff0000, v68
	v_lshlrev_b32_e32 v33, 16, v67
	v_lshlrev_b32_e32 v34, 16, v69
	v_and_b32_e32 v35, 0xffff0000, v67
	v_and_b32_e32 v36, 0xffff0000, v69
	s_waitcnt vmcnt(2)
	v_lshlrev_b32_e32 v21, 16, v70
	v_lshlrev_b32_e32 v22, 16, v72
	v_and_b32_e32 v23, 0xffff0000, v70
	v_and_b32_e32 v24, 0xffff0000, v72
	v_lshlrev_b32_e32 v25, 16, v71
	v_lshlrev_b32_e32 v26, 16, v73
	v_and_b32_e32 v27, 0xffff0000, v71
	v_and_b32_e32 v28, 0xffff0000, v73
	s_waitcnt vmcnt(1)
	v_lshlrev_b32_e32 v17, 16, v74
	v_lshlrev_b32_e32 v18, 16, v76
	v_and_b32_e32 v19, 0xffff0000, v74
	v_and_b32_e32 v20, 0xffff0000, v76
	v_lshlrev_b32_e32 v15, 16, v75
	v_lshlrev_b32_e32 v14, 16, v77
	v_and_b32_e32 v13, 0xffff0000, v75
	v_and_b32_e32 v12, 0xffff0000, v77
	s_waitcnt vmcnt(0)
	v_lshlrev_b32_e32 v11, 16, v78
	v_lshlrev_b32_e32 v10, 16, v80
	v_and_b32_e32 v9, 0xffff0000, v78
	v_and_b32_e32 v8, 0xffff0000, v80
	v_lshlrev_b32_e32 v7, 16, v79
	v_lshlrev_b32_e32 v6, 16, v81
	v_and_b32_e32 v5, 0xffff0000, v79
	v_and_b32_e32 v4, 0xffff0000, v81
	v_lshlrev_b32_e32 v62, 4, v188
	v_lshrrev_b32_e32 v53, 5, v188
	v_lshlrev_b32_e32 v53, 5, v53
	v_sub_u32_e32 v62, v62, v53
	v_mov_b32_e32 v63, 0
	v_lshl_add_u64 v[64:65], v[2:3], 0, v[62:63]
	global_load_dwordx4 v[54:57], v[64:65], off
	global_load_dwordx4 v[58:61], v[64:65], off offset:1024
	v_readlane_b32 s2, v253, 16
	s_lshl_b32 s2, s2, 14
	s_nop 1
	v_lshl_add_u32 v62, v188, 4, s2
	v_add_u32_e32 v52, s2, v53
	s_waitcnt vmcnt(0)
	ds_write_b128 v62, v[54:57]
	ds_write_b128 v62, v[58:61] offset:1024
	s_waitcnt lgkmcnt(0)
	s_cbranch_vccnz .LBB0_1503
	ds_read_b128 v[38:41], v52 offset:16
	ds_read_b128 v[42:45], v52
	v_xor_b32_e32 v37, 32, v235
	s_waitcnt lgkmcnt(0)
	v_fma_f32 v16, v42, v29, 0
	v_fmac_f32_e32 v16, v38, v30
	v_fmac_f32_e32 v16, v43, v31
	v_fmac_f32_e32 v16, v39, v32
	v_fmac_f32_e32 v16, v44, v33
	v_fmac_f32_e32 v16, v40, v34
	v_fmac_f32_e32 v16, v45, v35
	v_fmac_f32_e32 v16, v41, v36
	ds_read_b128 v[38:41], v52 offset:80
	ds_read_b128 v[42:45], v52 offset:64
	s_waitcnt lgkmcnt(0)
	v_fmac_f32_e32 v16, v42, v21
	v_fmac_f32_e32 v16, v38, v22
	v_fmac_f32_e32 v16, v43, v23
	v_fmac_f32_e32 v16, v39, v24
	v_fmac_f32_e32 v16, v44, v25
	v_fmac_f32_e32 v16, v40, v26
	v_fmac_f32_e32 v16, v45, v27
	v_fmac_f32_e32 v16, v41, v28
	ds_read_b128 v[38:41], v52 offset:144
	ds_read_b128 v[42:45], v52 offset:128
	s_waitcnt lgkmcnt(0)
	v_fmac_f32_e32 v16, v42, v17
	v_fmac_f32_e32 v16, v38, v18
	v_fmac_f32_e32 v16, v43, v19
	v_fmac_f32_e32 v16, v39, v20
	v_mov_b32_e32 v38, v40
	v_mov_b32_e32 v39, v44
	v_pk_mul_f32 v[38:39], v[38:39], v[14:15]
	v_mov_b32_e32 v44, v41
	v_add_f32_e32 v16, v39, v16
	v_add_f32_e32 v16, v38, v16
	v_pk_mul_f32 v[38:39], v[44:45], v[12:13]
	s_nop 0
	v_add_f32_e32 v16, v39, v16
	v_add_f32_e32 v16, v38, v16
	ds_read_b128 v[38:41], v52 offset:208
	ds_read_b128 v[42:45], v52 offset:192
	s_waitcnt lgkmcnt(1)
	v_mov_b32_e32 v46, v38
	s_waitcnt lgkmcnt(0)
	v_mov_b32_e32 v47, v42
	v_pk_mul_f32 v[46:47], v[46:47], v[10:11]
	v_mov_b32_e32 v42, v39
	v_add_f32_e32 v16, v47, v16
	v_add_f32_e32 v16, v46, v16
	v_pk_mul_f32 v[38:39], v[42:43], v[8:9]
	s_nop 0
	v_add_f32_e32 v16, v39, v16
	v_add_f32_e32 v16, v38, v16
	v_mov_b32_e32 v38, v40
	v_mov_b32_e32 v39, v44
	v_pk_mul_f32 v[38:39], v[38:39], v[6:7]
	v_mov_b32_e32 v44, v41
	v_add_f32_e32 v16, v39, v16
	v_add_f32_e32 v16, v38, v16
	v_pk_mul_f32 v[38:39], v[44:45], v[4:5]
	s_nop 0
	v_add_f32_e32 v16, v39, v16
	v_add_f32_e32 v16, v38, v16
	v_and_b32_e32 v38, 64, v235
	v_add_u32_e32 v38, 64, v38
	v_cmp_lt_i32_e32 vcc, v37, v38
	s_nop 1
	v_cndmask_b32_e32 v37, v235, v37, vcc
	v_lshlrev_b32_e32 v37, 2, v37
	ds_bpermute_b32 v37, v37, v16
	s_waitcnt lgkmcnt(0)
	v_add_f32_e32 v16, v16, v37

.Lnsa_ready:
	s_lshr_b32 s2, s40, 1
	s_and_b32 s2, s2, 0xfc
	s_and_b32 s3, s40, 3
	s_or_b32 s2, s2, s3
	s_xor_b32 s86, s2, 0xfc
	s_lshr_b32 s0, s40, 9
	v_readlane_b32 s1, v254, 63
	s_lshl_b32 s89, s86, 3
	v_bfe_u32 v129, v188, 2, 3
	s_or_b32 s0, s0, s1
	v_or_b32_e32 v197, s89, v129
	s_bfe_u32 s1, s40, 0x10002
	v_and_b32_e32 v130, 3, v188
	v_lshl_or_b32 v148, s0, 11, v197
	s_lshl_b32 s0, s0, 1
	v_lshl_or_b32 v128, s1, 2, v130
	s_or_b32 s36, s0, s1
	v_mov_b32_e32 v149, v1
	v_readlane_b32 s0, v254, 61
	v_lshlrev_b64 v[2:3], 10, v[148:149]
	v_readlane_b32 s1, v254, 62
	v_readlane_b32 s2, v254, 57
	v_lshlrev_b32_e32 v154, 3, v188
	v_lshl_add_u64 v[2:3], s[0:1], 0, v[2:3]
	s_lshl_b64 s[0:1], s[36:37], 14
	s_add_u32 s4, s2, s0
	v_readlane_b32 s2, v254, 55
	v_ashrrev_i32_e32 v155, 31, v154
	s_addc_u32 s5, s2, s1
	v_lshlrev_b64 v[152:153], 1, v[154:155]
	v_lshl_add_u64 v[42:43], s[4:5], 0, v[152:153]
	s_movk_i32 s2, 0x2000
	v_add_co_u32_e32 v46, vcc, s2, v42
	v_lshlrev_b32_e32 v0, 7, v128
	s_nop 0
	v_addc_co_u32_e32 v47, vcc, 0, v43, vcc
	v_lshl_add_u64 v[6:7], v[2:3], 0, v[0:1]
	global_load_dwordx4 v[2:5], v[46:47], off offset:-4096
	v_lshlrev_b32_e32 v8, 3, v196
	v_ashrrev_i32_e32 v9, 31, v8
	v_lshl_add_u64 v[52:53], v[8:9], 1, v[6:7]
	global_load_dwordx4 v[80:83], v[52:53], off
	global_load_dwordx4 v[18:21], v[42:43], off
	s_movk_i32 s3, 0x1000
	v_add_co_u32_e32 v50, vcc, s3, v42
	global_load_dwordx4 v[84:87], v[52:53], off offset:32
	s_nop 0
	v_addc_co_u32_e32 v51, vcc, 0, v43, vcc
	global_load_dwordx4 v[38:41], v[50:51], off offset:1024
	v_readlane_b32 s4, v254, 59
	v_readlane_b32 s5, v254, 60
	global_load_dwordx4 v[54:57], v[42:43], off offset:1024
	global_load_dwordx4 v[58:61], v[42:43], off offset:2048
	v_mov_b64_e32 v[6:7], s[4:5]
	s_movk_i32 s4, 0x60
	v_mad_u64_u32 v[6:7], s[4:5], v148, s4, v[6:7]
	v_readlane_b32 s4, v254, 53
	s_add_u32 s0, s4, s0
	v_readlane_b32 s4, v254, 51
	v_mul_u32_u24_e32 v0, 3, v128
	s_addc_u32 s1, s4, s1
	v_lshlrev_b32_e32 v0, 2, v0
	v_lshl_add_u64 v[48:49], s[0:1], 0, v[152:153]
	s_movk_i32 s0, 0x3000
	v_lshl_add_u64 v[150:151], v[6:7], 0, v[0:1]
	v_add_co_u32_e32 v44, vcc, s0, v48
	v_lshlrev_b32_e32 v66, 6, v196
	s_nop 0
	v_addc_co_u32_e32 v45, vcc, 0, v49, vcc
	global_load_dword v0, v[150:151], off
	global_load_dword v234, v[150:151], off offset:4
	global_load_dwordx4 v[34:37], v[44:45], off offset:3072
	global_load_dwordx4 v[88:91], v[52:53], off offset:64
	global_load_dwordx4 v[62:65], v[42:43], off offset:3072
	global_load_dwordx4 v[92:95], v[52:53], off offset:96
	v_or_b32_e32 v67, 31, v66
	v_or_b32_e32 v68, 47, v66
	v_cmp_le_i32_e32 vcc, v67, v197
	v_or_b32_e32 v69, 63, v66
	v_add_u32_e32 v70, 0x4f, v66
	v_add_u32_e32 v71, 0x9f, v66
	v_add_u32_e32 v72, 0xaf, v66
	v_add_u32_e32 v73, 0xbf, v66
	v_add_u32_e32 v74, 0xcf, v66
	v_add_u32_e32 v75, 0x19f, v66
	v_add_u32_e32 v76, 0x1af, v66
	v_lshl_add_u32 v206, v188, 2, s83
	v_cmp_eq_u32_e64 s[8:9], 0, v130
	s_waitcnt vmcnt(9)
	v_mfma_f32_32x32x16_bf16 v[18:33], v[18:21], v[80:83], 0
	v_mfma_f32_32x32x16_bf16 v[2:17], v[2:5], v[80:83], 0
	s_waitcnt vmcnt(7)
	v_mfma_f32_32x32x16_bf16 v[2:17], v[38:41], v[84:87], v[2:17]
	global_load_dwordx4 v[38:41], v[50:51], off offset:2048
	s_nop 0
	global_load_dwordx4 v[50:53], v[50:51], off offset:3072
	s_waitcnt vmcnt(8)
	v_mfma_f32_32x32x16_bf16 v[18:33], v[54:57], v[84:87], v[18:33]
	global_load_dwordx4 v[54:57], v[46:47], off
	s_waitcnt vmcnt(5)
	v_mfma_f32_32x32x16_bf16 v[18:33], v[58:61], v[88:91], v[18:33]
	v_add_u32_e32 v58, 0x11f, v66
	v_add_u32_e32 v59, 0x12f, v66
	v_add_u32_e32 v60, 0x13f, v66
	v_add_u32_e32 v61, 0x14f, v66
	s_waitcnt vmcnt(3)
	v_mfma_f32_32x32x16_bf16 v[18:33], v[62:65], v[92:95], v[18:33]
	s_waitcnt vmcnt(2)
	v_mfma_f32_32x32x16_bf16 v[2:17], v[38:41], v[88:91], v[2:17]
	s_nop 9
	v_mul_f32_e32 v18, 0x3e38aa3b, v18
	v_mul_f32_e32 v19, 0x3e38aa3b, v19
	v_cndmask_b32_e32 v62, v239, v18, vcc
	v_cmp_le_i32_e32 vcc, v68, v197
	v_mul_f32_e32 v20, 0x3e38aa3b, v20
	v_mul_f32_e32 v21, 0x3e38aa3b, v21
	v_cndmask_b32_e32 v63, v239, v19, vcc
	v_cmp_le_i32_e32 vcc, v69, v197
	v_mul_f32_e32 v22, 0x3e38aa3b, v22
	v_mul_f32_e32 v23, 0x3e38aa3b, v23
	v_cndmask_b32_e32 v64, v239, v20, vcc
	v_cmp_le_i32_e32 vcc, v70, v197
	v_mul_f32_e32 v24, 0x3e38aa3b, v24
	v_mul_f32_e32 v25, 0x3e38aa3b, v25
	v_cndmask_b32_e32 v65, v239, v21, vcc
	v_cmp_le_i32_e32 vcc, v71, v197
	v_mul_f32_e32 v26, 0x3e38aa3b, v26
	v_mul_f32_e32 v27, 0x3e38aa3b, v27
	v_cndmask_b32_e32 v67, v239, v22, vcc
	v_cmp_le_i32_e32 vcc, v72, v197
	v_mul_f32_e32 v28, 0x3e38aa3b, v28
	global_load_dwordx4 v[38:41], v[46:47], off offset:2048
	v_cndmask_b32_e32 v68, v239, v23, vcc
	v_cmp_le_i32_e32 vcc, v73, v197
	s_waitcnt vmcnt(2)
	v_mfma_f32_32x32x16_bf16 v[2:17], v[50:53], v[92:95], v[2:17]
	v_mul_f32_e32 v29, 0x3e38aa3b, v29
	v_cndmask_b32_e32 v69, v239, v24, vcc
	v_cmp_le_i32_e32 vcc, v74, v197
	v_mul_f32_e32 v30, 0x3e38aa3b, v30
	v_mul_f32_e32 v31, 0x3e38aa3b, v31
	v_cndmask_b32_e32 v70, v239, v25, vcc
	v_cmp_le_i32_e32 vcc, v58, v197
	v_add_u32_e32 v19, 0x1bf, v66
	global_load_dwordx4 v[50:53], v[46:47], off offset:3072
	v_cndmask_b32_e32 v71, v239, v26, vcc
	v_cmp_le_i32_e32 vcc, v59, v197
	v_mul_f32_e32 v20, 0x3e38aa3b, v32
	v_mul_f32_e32 v2, 0x3e38aa3b, v2
	v_cndmask_b32_e32 v72, v239, v27, vcc
	v_cmp_le_i32_e32 vcc, v60, v197
	v_max3_f32 v18, v62, s69, v63
	v_max3_f32 v18, v18, v64, v65
	v_cndmask_b32_e32 v73, v239, v28, vcc
	v_cmp_le_i32_e32 vcc, v61, v197
	global_load_dwordx4 v[58:61], v[46:47], off offset:1024
	v_mul_f32_e32 v3, 0x3e38aa3b, v3
	v_cndmask_b32_e32 v74, v239, v29, vcc
	v_cmp_le_i32_e32 vcc, v75, v197
	v_max3_f32 v18, v18, v67, v68
	v_max3_f32 v18, v18, v69, v70
	v_cndmask_b32_e32 v75, v239, v30, vcc
	v_cmp_le_i32_e32 vcc, v76, v197
	v_mul_f32_e32 v4, 0x3e38aa3b, v4
	v_max3_f32 v18, v18, v71, v72
	v_cndmask_b32_e32 v76, v239, v31, vcc
	v_cmp_le_i32_e32 vcc, v19, v197
	v_add_u32_e32 v19, 0x1cf, v66
	v_max3_f32 v18, v18, v73, v74
	v_cndmask_b32_e32 v77, v239, v20, vcc
	v_mul_f32_e32 v20, 0x3e38aa3b, v33
	v_cmp_le_i32_e32 vcc, v19, v197
	v_add_u32_e32 v19, 0x21f, v66
	v_max3_f32 v18, v18, v75, v76
	v_cndmask_b32_e32 v78, v239, v20, vcc
	v_cmp_le_i32_e32 vcc, v19, v197
	v_max3_f32 v18, v18, v77, v78
	s_nop 0
	v_cndmask_b32_e32 v46, v239, v2, vcc
	v_add_u32_e32 v2, 0x22f, v66
	v_cmp_le_i32_e32 vcc, v2, v197
	s_nop 1
	v_cndmask_b32_e32 v47, v239, v3, vcc
	v_add_u32_e32 v3, 0x23f, v66
	v_cmp_le_i32_e32 vcc, v3, v197
	v_add_u32_e32 v3, 0x24f, v66
	v_max3_f32 v2, v18, v46, v47
	v_cndmask_b32_e32 v96, v239, v4, vcc
	v_mul_f32_e32 v4, 0x3e38aa3b, v5
	v_cmp_le_i32_e32 vcc, v3, v197
	v_add_u32_e32 v3, 0x29f, v66
	s_waitcnt vmcnt(3)
	v_mfma_f32_32x32x16_bf16 v[18:33], v[54:57], v[80:83], 0
	v_cndmask_b32_e32 v97, v239, v4, vcc
	v_mul_f32_e32 v4, 0x3e38aa3b, v6
	v_cmp_le_i32_e32 vcc, v3, v197
	v_add_u32_e32 v3, 0x2af, v66
	v_max3_f32 v2, v2, v96, v97
	v_cndmask_b32_e32 v100, v239, v4, vcc
	v_mul_f32_e32 v4, 0x3e38aa3b, v7
	v_cmp_le_i32_e32 vcc, v3, v197
	v_add_u32_e32 v3, 0x2bf, v66
	s_waitcnt vmcnt(0)
	v_mfma_f32_32x32x16_bf16 v[18:33], v[58:61], v[84:87], v[18:33]
	v_cndmask_b32_e32 v101, v239, v4, vcc
	v_mul_f32_e32 v4, 0x3e38aa3b, v8
	v_cmp_le_i32_e32 vcc, v3, v197
	v_add_u32_e32 v3, 0x2cf, v66
	v_max3_f32 v2, v2, v100, v101
	v_cndmask_b32_e32 v102, v239, v4, vcc
	v_mul_f32_e32 v4, 0x3e38aa3b, v9
	v_cmp_le_i32_e32 vcc, v3, v197
	v_add_u32_e32 v3, 0x31f, v66
	v_mfma_f32_32x32x16_bf16 v[18:33], v[38:41], v[88:91], v[18:33]
	v_cndmask_b32_e32 v103, v239, v4, vcc
	v_mul_f32_e32 v4, 0x3e38aa3b, v10
	v_cmp_le_i32_e32 vcc, v3, v197
	v_add_u32_e32 v3, 0x32f, v66
	v_max3_f32 v2, v2, v102, v103
	v_cndmask_b32_e32 v104, v239, v4, vcc
	v_mul_f32_e32 v4, 0x3e38aa3b, v11
	v_cmp_le_i32_e32 vcc, v3, v197
	v_mul_f32_e32 v3, 0x3e38aa3b, v12
	v_mfma_f32_32x32x16_bf16 v[18:33], v[50:53], v[92:95], v[18:33]
	v_cndmask_b32_e32 v105, v239, v4, vcc
	v_max3_f32 v8, v2, v104, v105
	v_add_u32_e32 v2, 0x33f, v66
	v_cmp_le_i32_e32 vcc, v2, v197
	v_add_u32_e32 v2, 0x34f, v66
	v_add_u32_e32 v9, 0x39f, v66
	v_cndmask_b32_e32 v106, v239, v3, vcc
	v_mul_f32_e32 v3, 0x3e38aa3b, v13
	v_cmp_le_i32_e32 vcc, v2, v197
	v_mul_f32_e32 v10, 0x3e38aa3b, v14
	s_nop 1
	v_mul_f32_e32 v29, 0x3e38aa3b, v29
	v_cndmask_b32_e32 v107, v239, v3, vcc
	v_add_co_u32_e32 v6, vcc, s0, v42
	v_max3_f32 v8, v8, v106, v107
	s_nop 0
	v_addc_co_u32_e32 v7, vcc, 0, v43, vcc
	global_load_dwordx4 v[2:5], v[6:7], off
	global_load_dwordx4 v[54:57], v[6:7], off offset:1024
	global_load_dwordx4 v[58:61], v[6:7], off offset:2048
	global_load_dwordx4 v[38:41], v[6:7], off offset:3072
	v_cmp_le_i32_e32 vcc, v9, v197
	v_add_u32_e32 v9, 0x3af, v66
	v_add_u32_e32 v7, 0x41f, v66
	v_cndmask_b32_e32 v108, v239, v10, vcc
	v_mul_f32_e32 v10, 0x3e38aa3b, v15
	v_cmp_le_i32_e32 vcc, v9, v197
	v_add_u32_e32 v9, 0x3bf, v66
	v_mul_f32_e32 v30, 0x3e38aa3b, v30
	v_cndmask_b32_e32 v109, v239, v10, vcc
	v_mul_f32_e32 v10, 0x3e38aa3b, v16
	v_cmp_le_i32_e32 vcc, v9, v197
	v_add_u32_e32 v9, 0x3cf, v66
	v_max3_f32 v8, v8, v108, v109
	v_cndmask_b32_e32 v110, v239, v10, vcc
	v_mul_f32_e32 v10, 0x3e38aa3b, v17
	v_cmp_le_i32_e32 vcc, v9, v197
	v_mul_f32_e32 v31, 0x3e38aa3b, v31
	v_mul_f32_e32 v32, 0x3e38aa3b, v32
	v_cndmask_b32_e32 v111, v239, v10, vcc
	v_max3_f32 v6, v8, v110, v111
	v_mul_f32_e32 v8, 0x3e38aa3b, v18
	v_cmp_le_i32_e32 vcc, v7, v197
	v_add_u32_e32 v7, 0x42f, v66
	v_mul_f32_e32 v33, 0x3e38aa3b, v33
	v_cndmask_b32_e32 v50, v239, v8, vcc
	v_mul_f32_e32 v8, 0x3e38aa3b, v19
	v_cmp_le_i32_e32 vcc, v7, v197
	v_add_u32_e32 v7, 0x43f, v66
	v_add_u32_e32 v19, 0x54f, v66
	v_cndmask_b32_e32 v51, v239, v8, vcc
	v_mul_f32_e32 v8, 0x3e38aa3b, v20
	v_cmp_le_i32_e32 vcc, v7, v197
	v_add_u32_e32 v7, 0x44f, v66
	v_max3_f32 v6, v6, v50, v51
	v_cndmask_b32_e32 v20, v239, v8, vcc
	v_mul_f32_e32 v8, 0x3e38aa3b, v21
	v_cmp_le_i32_e32 vcc, v7, v197
	v_add_u32_e32 v7, 0x49f, v66
	s_nop 0
	v_cndmask_b32_e32 v21, v239, v8, vcc
	v_mul_f32_e32 v8, 0x3e38aa3b, v22
	v_cmp_le_i32_e32 vcc, v7, v197
	v_add_u32_e32 v7, 0x4af, v66
	v_max3_f32 v6, v6, v20, v21
	v_cndmask_b32_e32 v22, v239, v8, vcc
	v_mul_f32_e32 v8, 0x3e38aa3b, v23
	v_cmp_le_i32_e32 vcc, v7, v197
	v_add_u32_e32 v7, 0x4bf, v66
	s_nop 0
	v_cndmask_b32_e32 v23, v239, v8, vcc
	v_mul_f32_e32 v8, 0x3e38aa3b, v24
	v_cmp_le_i32_e32 vcc, v7, v197
	v_add_u32_e32 v7, 0x4cf, v66
	v_max3_f32 v6, v6, v22, v23
	v_cndmask_b32_e32 v24, v239, v8, vcc
	v_mul_f32_e32 v8, 0x3e38aa3b, v25
	v_cmp_le_i32_e32 vcc, v7, v197
	v_add_u32_e32 v7, 0x51f, v66
	s_nop 0
	v_cndmask_b32_e32 v25, v239, v8, vcc
	v_mul_f32_e32 v8, 0x3e38aa3b, v26
	v_cmp_le_i32_e32 vcc, v7, v197
	v_add_u32_e32 v7, 0x52f, v66
	v_max3_f32 v6, v6, v24, v25
	v_cndmask_b32_e32 v26, v239, v8, vcc
	v_mul_f32_e32 v8, 0x3e38aa3b, v27
	v_cmp_le_i32_e32 vcc, v7, v197
	v_mul_f32_e32 v7, 0x3e38aa3b, v28
	s_nop 0
	v_cndmask_b32_e32 v27, v239, v8, vcc
	v_max3_f32 v18, v6, v26, v27
	v_add_u32_e32 v6, 0x53f, v66
	v_cmp_le_i32_e32 vcc, v6, v197
	s_nop 1
	v_cndmask_b32_e32 v28, v239, v7, vcc
	s_waitcnt vmcnt(3)
	v_mfma_f32_32x32x16_bf16 v[2:17], v[2:5], v[80:83], 0
	v_cmp_le_i32_e32 vcc, v19, v197
	v_add_u32_e32 v19, 0x59f, v66
	s_nop 0
	v_cndmask_b32_e32 v29, v239, v29, vcc
	v_cmp_le_i32_e32 vcc, v19, v197
	v_add_u32_e32 v19, 0x5af, v66
	v_max3_f32 v18, v18, v28, v29
	s_waitcnt vmcnt(2)
	v_mfma_f32_32x32x16_bf16 v[2:17], v[54:57], v[84:87], v[2:17]
	v_cndmask_b32_e32 v30, v239, v30, vcc
	v_cmp_le_i32_e32 vcc, v19, v197
	v_add_u32_e32 v19, 0x5bf, v66
	s_nop 0
	v_cndmask_b32_e32 v31, v239, v31, vcc
	v_cmp_le_i32_e32 vcc, v19, v197
	v_add_u32_e32 v19, 0x5cf, v66
	s_waitcnt vmcnt(1)
	v_mfma_f32_32x32x16_bf16 v[2:17], v[58:61], v[88:91], v[2:17]
	v_cndmask_b32_e32 v32, v239, v32, vcc
	v_cmp_le_i32_e32 vcc, v19, v197
	v_add_u32_e32 v19, 0x61f, v66
	v_max3_f32 v18, v18, v30, v31
	v_cndmask_b32_e32 v33, v239, v33, vcc
	v_cmp_le_i32_e32 vcc, v19, v197
	v_max3_f32 v18, v18, v32, v33
	s_waitcnt vmcnt(0)
	v_mfma_f32_32x32x16_bf16 v[2:17], v[38:41], v[92:95], v[2:17]
	s_nop 11
	v_mul_f32_e32 v2, 0x3e38aa3b, v2
	v_cndmask_b32_e32 v114, v239, v2, vcc
	v_add_u32_e32 v2, 0x62f, v66
	v_mul_f32_e32 v3, 0x3e38aa3b, v3
	v_cmp_le_i32_e32 vcc, v2, v197
	v_mul_f32_e32 v4, 0x3e38aa3b, v4
	s_nop 0
	v_cndmask_b32_e32 v115, v239, v3, vcc
	v_add_u32_e32 v3, 0x63f, v66
	v_cmp_le_i32_e32 vcc, v3, v197
	v_add_u32_e32 v3, 0x64f, v66
	v_max3_f32 v2, v18, v114, v115
	v_cndmask_b32_e32 v116, v239, v4, vcc
	v_mul_f32_e32 v4, 0x3e38aa3b, v5
	v_cmp_le_i32_e32 vcc, v3, v197
	v_add_u32_e32 v3, 0x69f, v66
	s_nop 0
	v_cndmask_b32_e32 v117, v239, v4, vcc
	v_mul_f32_e32 v4, 0x3e38aa3b, v6
	v_cmp_le_i32_e32 vcc, v3, v197
	v_add_u32_e32 v3, 0x6af, v66
	v_max3_f32 v2, v2, v116, v117
	v_cndmask_b32_e32 v120, v239, v4, vcc
	v_mul_f32_e32 v4, 0x3e38aa3b, v7
	v_cmp_le_i32_e32 vcc, v3, v197
	v_add_u32_e32 v3, 0x6bf, v66
	s_nop 0
	v_cndmask_b32_e32 v121, v239, v4, vcc
	v_mul_f32_e32 v4, 0x3e38aa3b, v8
	v_cmp_le_i32_e32 vcc, v3, v197
	v_add_u32_e32 v3, 0x6cf, v66
	v_max3_f32 v2, v2, v120, v121
	v_cndmask_b32_e32 v122, v239, v4, vcc
	v_mul_f32_e32 v4, 0x3e38aa3b, v9
	v_cmp_le_i32_e32 vcc, v3, v197
	v_add_u32_e32 v3, 0x71f, v66
	s_nop 0
	v_cndmask_b32_e32 v123, v239, v4, vcc
	v_mul_f32_e32 v4, 0x3e38aa3b, v10
	v_cmp_le_i32_e32 vcc, v3, v197
	v_add_u32_e32 v3, 0x72f, v66
	v_max3_f32 v2, v2, v122, v123
	v_cndmask_b32_e32 v132, v239, v4, vcc
	v_mul_f32_e32 v4, 0x3e38aa3b, v11
	v_cmp_le_i32_e32 vcc, v3, v197
	v_add_u32_e32 v3, 0x73f, v66
	s_nop 0
	v_cndmask_b32_e32 v133, v239, v4, vcc
	v_mul_f32_e32 v4, 0x3e38aa3b, v12
	v_cmp_le_i32_e32 vcc, v3, v197
	v_add_u32_e32 v3, 0x74f, v66
	v_max3_f32 v2, v2, v132, v133
	v_cndmask_b32_e32 v134, v239, v4, vcc
	v_mul_f32_e32 v4, 0x3e38aa3b, v13
	v_cmp_le_i32_e32 vcc, v3, v197
	v_add_u32_e32 v3, 0x79f, v66
	s_nop 0
	v_cndmask_b32_e32 v135, v239, v4, vcc
	v_mul_f32_e32 v4, 0x3e38aa3b, v14
	v_cmp_le_i32_e32 vcc, v3, v197
	v_add_u32_e32 v3, 0x7af, v66
	v_max3_f32 v2, v2, v134, v135
	v_cndmask_b32_e32 v14, v239, v4, vcc
	v_mul_f32_e32 v4, 0x3e38aa3b, v15
	v_cmp_le_i32_e32 vcc, v3, v197
	v_add_u32_e32 v3, 0x7bf, v66
	s_nop 0
	v_cndmask_b32_e32 v15, v239, v4, vcc
	v_mul_f32_e32 v4, 0x3e38aa3b, v16
	v_cmp_le_i32_e32 vcc, v3, v197
	v_add_u32_e32 v3, 0x7cf, v66
	v_max3_f32 v2, v2, v14, v15
	v_cndmask_b32_e32 v16, v239, v4, vcc
	v_mul_f32_e32 v4, 0x3e38aa3b, v17
	v_cmp_le_i32_e32 vcc, v3, v197
	v_xor_b32_e32 v3, 32, v235
	s_nop 0
	v_cndmask_b32_e32 v17, v239, v4, vcc
	v_and_b32_e32 v4, 64, v235
	v_add_u32_e32 v131, 64, v4
	v_cmp_lt_i32_e32 vcc, v3, v131
	v_max3_f32 v2, v2, v16, v17
	s_nop 0
	v_cndmask_b32_e32 v3, v235, v3, vcc
	v_lshlrev_b32_e32 v205, 2, v3
	ds_bpermute_b32 v3, v205, v2
	s_waitcnt lgkmcnt(0)
	v_max_f32_e32 v3, v3, v3
	v_max_f32_e32 v2, v2, v3
	v_cmp_neq_f32_e32 vcc, s69, v2
	s_nop 1
	v_cndmask_b32_e32 v136, 0, v2, vcc
	v_sub_f32_e32 v2, v62, v136
	v_exp_f32_e32 v2, v2
	v_sub_f32_e32 v3, v63, v136
	v_exp_f32_e32 v3, v3
	v_sub_f32_e32 v4, v64, v136
	v_exp_f32_e32 v4, v4
	v_sub_f32_e32 v5, v65, v136
	v_exp_f32_e32 v5, v5
	v_add_f32_e32 v6, 0, v2
	v_add_f32_e32 v6, v3, v6
	v_add_f32_e32 v6, v4, v6
	v_add_f32_e32 v10, v5, v6
	v_sub_f32_e32 v6, v67, v136
	v_exp_f32_e32 v6, v6
	v_sub_f32_e32 v7, v68, v136
	v_exp_f32_e32 v7, v7
	v_sub_f32_e32 v8, v69, v136
	v_exp_f32_e32 v8, v8
	v_sub_f32_e32 v9, v70, v136
	v_exp_f32_e32 v9, v9
	v_sub_f32_e32 v11, v71, v136
	v_add_f32_e32 v10, v6, v10
	v_exp_f32_e32 v18, v11
	v_sub_f32_e32 v11, v72, v136
	v_add_f32_e32 v10, v7, v10
	v_exp_f32_e32 v19, v11
	v_sub_f32_e32 v11, v73, v136
	v_add_f32_e32 v10, v8, v10
	v_exp_f32_e32 v38, v11
	v_sub_f32_e32 v11, v74, v136
	v_add_f32_e32 v10, v9, v10
	v_exp_f32_e32 v39, v11
	v_sub_f32_e32 v11, v75, v136
	v_add_f32_e32 v10, v18, v10
	v_exp_f32_e32 v58, v11
	v_sub_f32_e32 v11, v76, v136
	v_add_f32_e32 v10, v19, v10
	v_exp_f32_e32 v59, v11
	v_sub_f32_e32 v11, v77, v136
	v_add_f32_e32 v10, v38, v10
	v_exp_f32_e32 v60, v11
	v_sub_f32_e32 v11, v78, v136
	v_add_f32_e32 v10, v39, v10
	v_exp_f32_e32 v61, v11
	v_sub_f32_e32 v11, v46, v136
	v_add_f32_e32 v10, v58, v10
	v_exp_f32_e32 v78, v11
	v_sub_f32_e32 v11, v47, v136
	v_add_f32_e32 v10, v59, v10
	v_exp_f32_e32 v79, v11
	v_sub_f32_e32 v11, v96, v136
	v_add_f32_e32 v10, v60, v10
	v_exp_f32_e32 v98, v11
	v_sub_f32_e32 v11, v97, v136
	v_add_f32_e32 v10, v61, v10
	v_exp_f32_e32 v99, v11
	v_sub_f32_e32 v11, v100, v136
	v_add_f32_e32 v10, v78, v10
	v_exp_f32_e32 v126, v11
	v_sub_f32_e32 v11, v101, v136
	v_add_f32_e32 v10, v79, v10
	v_exp_f32_e32 v127, v11
	v_sub_f32_e32 v11, v102, v136
	v_add_f32_e32 v10, v98, v10
	v_exp_f32_e32 v62, v11
	v_sub_f32_e32 v11, v103, v136
	v_add_f32_e32 v10, v99, v10
	v_exp_f32_e32 v63, v11
	v_sub_f32_e32 v11, v104, v136
	v_add_f32_e32 v10, v126, v10
	v_exp_f32_e32 v42, v11
	v_sub_f32_e32 v11, v105, v136
	v_add_f32_e32 v10, v127, v10
	v_exp_f32_e32 v43, v11
	v_sub_f32_e32 v11, v106, v136
	v_add_f32_e32 v10, v62, v10
	v_exp_f32_e32 v54, v11
	v_sub_f32_e32 v11, v107, v136
	v_add_f32_e32 v10, v63, v10
	v_exp_f32_e32 v55, v11
	v_sub_f32_e32 v11, v108, v136
	v_add_f32_e32 v10, v42, v10
	v_exp_f32_e32 v96, v11
	v_sub_f32_e32 v11, v109, v136
	v_add_f32_e32 v10, v43, v10
	v_exp_f32_e32 v97, v11
	v_sub_f32_e32 v11, v110, v136
	v_add_f32_e32 v10, v54, v10
	v_exp_f32_e32 v124, v11
	v_sub_f32_e32 v11, v111, v136
	v_add_f32_e32 v10, v55, v10
	v_exp_f32_e32 v125, v11
	v_sub_f32_e32 v11, v50, v136
	v_add_f32_e32 v10, v96, v10
	v_exp_f32_e32 v50, v11
	v_sub_f32_e32 v11, v51, v136
	v_add_f32_e32 v10, v97, v10
	v_exp_f32_e32 v51, v11
	v_sub_f32_e32 v11, v20, v136
	v_add_f32_e32 v10, v124, v10
	v_exp_f32_e32 v76, v11
	v_sub_f32_e32 v11, v21, v136
	v_add_f32_e32 v10, v125, v10
	v_exp_f32_e32 v77, v11
	v_sub_f32_e32 v11, v22, v136
	v_add_f32_e32 v10, v50, v10
	v_exp_f32_e32 v52, v11
	v_sub_f32_e32 v11, v23, v136
	v_add_f32_e32 v10, v51, v10
	v_exp_f32_e32 v53, v11
	v_sub_f32_e32 v11, v24, v136
	v_add_f32_e32 v10, v76, v10
	v_exp_f32_e32 v56, v11
	v_sub_f32_e32 v11, v25, v136
	v_add_f32_e32 v10, v77, v10
	v_exp_f32_e32 v57, v11
	v_sub_f32_e32 v11, v26, v136
	v_add_f32_e32 v10, v52, v10
	v_exp_f32_e32 v40, v11
	v_sub_f32_e32 v11, v27, v136
	v_add_f32_e32 v10, v53, v10
	v_exp_f32_e32 v41, v11
	v_sub_f32_e32 v11, v28, v136
	v_add_f32_e32 v10, v56, v10
	v_exp_f32_e32 v46, v11
	v_sub_f32_e32 v11, v29, v136
	v_add_f32_e32 v10, v57, v10
	v_exp_f32_e32 v47, v11
	v_sub_f32_e32 v11, v30, v136
	v_add_f32_e32 v10, v40, v10
	v_exp_f32_e32 v112, v11
	v_sub_f32_e32 v11, v31, v136
	v_add_f32_e32 v10, v41, v10
	v_exp_f32_e32 v113, v11
	v_sub_f32_e32 v11, v32, v136
	v_add_f32_e32 v10, v46, v10
	v_exp_f32_e32 v118, v11
	v_sub_f32_e32 v11, v33, v136
	v_add_f32_e32 v10, v47, v10
	v_exp_f32_e32 v119, v11
	v_add_f32_e32 v10, v112, v10
	v_add_f32_e32 v10, v113, v10
	v_add_f32_e32 v10, v118, v10
	v_add_f32_e32 v20, v119, v10
	v_sub_f32_e32 v10, v114, v136
	v_exp_f32_e32 v64, v10
	v_sub_f32_e32 v10, v115, v136
	v_sub_f32_e32 v21, v116, v136
	v_exp_f32_e32 v65, v10
	global_load_dwordx4 v[10:13], v[48:49], off
	v_exp_f32_e32 v72, v21
	v_sub_f32_e32 v21, v117, v136
	v_exp_f32_e32 v73, v21
	v_sub_f32_e32 v21, v120, v136
	v_exp_f32_e32 v66, v21
	v_sub_f32_e32 v21, v121, v136
	v_exp_f32_e32 v67, v21
	v_sub_f32_e32 v21, v122, v136
	v_exp_f32_e32 v74, v21
	v_sub_f32_e32 v21, v123, v136
	v_exp_f32_e32 v75, v21
	v_sub_f32_e32 v21, v132, v136
	v_exp_f32_e32 v68, v21
	v_sub_f32_e32 v21, v133, v136
	v_exp_f32_e32 v69, v21
	v_sub_f32_e32 v21, v134, v136
	v_exp_f32_e32 v70, v21
	v_sub_f32_e32 v21, v135, v136
	global_load_dwordx4 v[132:135], v[48:49], off offset:2048
	v_add_f32_e32 v20, v64, v20
	v_add_f32_e32 v20, v65, v20
	v_add_f32_e32 v20, v72, v20
	v_add_f32_e32 v20, v73, v20
	v_add_f32_e32 v20, v66, v20
	v_add_f32_e32 v20, v67, v20
	v_add_f32_e32 v20, v74, v20
	v_add_f32_e32 v20, v75, v20
	v_exp_f32_e32 v71, v21
	v_sub_f32_e32 v14, v14, v136
	v_add_f32_e32 v20, v68, v20
	v_exp_f32_e32 v102, v14
	v_sub_f32_e32 v14, v15, v136
	v_add_f32_e32 v20, v69, v20
	v_exp_f32_e32 v103, v14
	v_sub_f32_e32 v14, v16, v136
	v_add_f32_e32 v20, v70, v20
	v_exp_f32_e32 v106, v14
	v_sub_f32_e32 v14, v17, v136
	v_add_f32_e32 v20, v71, v20
	v_exp_f32_e32 v107, v14
	v_add_f32_e32 v14, v102, v20
	v_add_f32_e32 v14, v103, v14
	v_add_f32_e32 v14, v106, v14
	v_add_f32_e32 v14, v107, v14
	ds_bpermute_b32 v15, v205, v14
	global_load_dwordx4 v[20:23], v[48:49], off offset:1024
	global_load_dwordx4 v[136:139], v[48:49], off offset:3072
	s_waitcnt lgkmcnt(0)
	v_add_f32_e32 v14, v14, v15
	v_max_f32_e32 v14, 0xda24260, v14
	v_div_scale_f32 v15, s[0:1], v14, v14, 1.0
	v_rcp_f32_e32 v16, v15
	s_nop 0
	v_fma_f32 v17, -v15, v16, 1.0
	v_fmac_f32_e32 v16, v17, v16
	v_div_scale_f32 v17, vcc, 1.0, v14, 1.0
	v_mul_f32_e32 v24, v17, v16
	v_fma_f32 v25, -v15, v24, v17
	v_fmac_f32_e32 v24, v25, v16
	v_fma_f32 v15, -v15, v24, v17
	v_div_fmas_f32 v15, v15, v16, v24
	v_div_fixup_f32 v156, v15, v14, 1.0
	v_pk_mul_f32 v[120:121], v[2:3], v[156:157] op_sel_hi:[1,0]
	v_pk_mul_f32 v[122:123], v[4:5], v[156:157] op_sel_hi:[1,0]
	v_pk_mul_f32 v[110:111], v[6:7], v[156:157] op_sel_hi:[1,0]
	v_pk_mul_f32 v[116:117], v[8:9], v[156:157] op_sel_hi:[1,0]
	v_cvt_pk_bf16_f32 v24, v120, v121
	v_cvt_pk_bf16_f32 v25, v122, v123
	v_cvt_pk_bf16_f32 v26, v110, v111
	v_cvt_pk_bf16_f32 v27, v116, v117
	v_add_co_u32_e32 v158, vcc, s2, v48
	s_nop 1
	v_addc_co_u32_e32 v159, vcc, 0, v49, vcc
	global_load_dwordx4 v[140:143], v[158:159], off offset:-4096
	global_load_dwordx4 v[210:213], v[158:159], off offset:-3072
	global_load_dwordx4 v[218:221], v[158:159], off offset:-2048
	global_load_dwordx4 v[222:225], v[158:159], off offset:-1024
	global_load_dwordx4 v[214:217], v[158:159], off
	global_load_dwordx4 v[184:187], v[158:159], off offset:1024
	global_load_dwordx4 v[230:233], v[158:159], off offset:2048
	global_load_dwordx4 v[192:195], v[158:159], off offset:3072
	global_load_dwordx4 v[226:229], v[44:45], off
	s_waitcnt vmcnt(12)
	v_mfma_f32_32x32x16_bf16 v[2:17], v[10:13], v[24:27], 0
	v_mul_f32_e64 v108, v18, v156
	v_mul_f32_e64 v109, v19, v156
	v_mul_f32_e64 v114, v38, v156
	v_mul_f32_e64 v115, v39, v156
	v_pk_mul_f32 v[100:101], v[58:59], v[156:157] op_sel_hi:[1,0]
	v_pk_mul_f32 v[104:105], v[60:61], v[156:157] op_sel_hi:[1,0]
	v_add_co_u32_e32 v160, vcc, s3, v48
	v_cvt_pk_bf16_f32 v144, v108, v109
	v_cvt_pk_bf16_f32 v145, v114, v115
	v_cvt_pk_bf16_f32 v146, v100, v101
	v_cvt_pk_bf16_f32 v147, v104, v105
	v_addc_co_u32_e32 v161, vcc, 0, v49, vcc
	s_waitcnt vmcnt(11)
	v_mfma_f32_32x32x16_bf16 v[2:17], v[132:135], v[144:147], v[2:17]
	v_mul_f32_e64 v58, v78, v156
	v_mul_f32_e64 v59, v79, v156
	v_mul_f32_e64 v60, v98, v156
	v_mul_f32_e64 v61, v99, v156
	v_pk_mul_f32 v[38:39], v[126:127], v[156:157] op_sel_hi:[1,0]
	v_pk_mul_f32 v[62:63], v[62:63], v[156:157] op_sel_hi:[1,0]
	v_pk_mul_f32 v[78:79], v[42:43], v[156:157] op_sel_hi:[1,0]
	v_pk_mul_f32 v[98:99], v[54:55], v[156:157] op_sel_hi:[1,0]
	s_waitcnt vmcnt(10)
	v_mfma_f32_32x32x16_bf16 v[18:33], v[20:23], v[24:27], 0
	v_mul_f32_e64 v42, v96, v156
	v_mul_f32_e64 v43, v97, v156
	v_mul_f32_e64 v48, v124, v156
	v_mul_f32_e64 v49, v125, v156
	v_cvt_pk_bf16_f32 v124, v78, v79
	v_cvt_pk_bf16_f32 v125, v98, v99
	v_cvt_pk_bf16_f32 v126, v42, v43
	v_cvt_pk_bf16_f32 v127, v48, v49
	v_pk_mul_f32 v[50:51], v[50:51], v[156:157] op_sel_hi:[1,0]
	s_waitcnt vmcnt(9)
	v_mfma_f32_32x32x16_bf16 v[18:33], v[136:139], v[144:147], v[18:33]
	v_cvt_pk_bf16_f32 v136, v58, v59
	v_cvt_pk_bf16_f32 v137, v60, v61
	v_cvt_pk_bf16_f32 v138, v38, v39
	v_cvt_pk_bf16_f32 v139, v62, v63
	v_pk_mul_f32 v[54:55], v[76:77], v[156:157] op_sel_hi:[1,0]
	v_pk_mul_f32 v[52:53], v[52:53], v[156:157] op_sel_hi:[1,0]
	s_waitcnt vmcnt(8)
	v_mfma_f32_32x32x16_bf16 v[2:17], v[140:143], v[136:139], v[2:17]
	global_load_dwordx4 v[140:143], v[44:45], off offset:1024
	v_mul_f32_e64 v56, v56, v156
	v_mul_f32_e64 v57, v57, v156
	v_mul_f32_e64 v76, v40, v156
	v_mul_f32_e64 v77, v41, v156
	v_pk_mul_f32 v[96:97], v[46:47], v[156:157] op_sel_hi:[1,0]
	v_pk_mul_f32 v[40:41], v[112:113], v[156:157] op_sel_hi:[1,0]
	v_pk_mul_f32 v[46:47], v[118:119], v[156:157] op_sel_hi:[1,0]
	v_pk_mul_f32 v[64:65], v[64:65], v[156:157] op_sel_hi:[1,0]
	s_waitcnt vmcnt(8)
	v_mfma_f32_32x32x16_bf16 v[18:33], v[210:213], v[136:139], v[18:33]
	global_load_dwordx4 v[210:213], v[44:45], off offset:2048
	v_mul_f32_e64 v72, v72, v156
	v_mul_f32_e64 v73, v73, v156
	v_mul_f32_e64 v66, v66, v156
	v_mul_f32_e64 v67, v67, v156
	v_pk_mul_f32 v[74:75], v[74:75], v[156:157] op_sel_hi:[1,0]
	v_pk_mul_f32 v[112:113], v[68:69], v[156:157] op_sel_hi:[1,0]
	v_pk_mul_f32 v[70:71], v[70:71], v[156:157] op_sel_hi:[1,0]
	s_waitcnt vmcnt(8)
	v_mfma_f32_32x32x16_bf16 v[2:17], v[218:221], v[124:127], v[2:17]
	v_mul_f32_e64 v68, v106, v156
	v_mul_f32_e64 v69, v107, v156
	s_waitcnt vmcnt(7)
	v_mfma_f32_32x32x16_bf16 v[18:33], v[222:225], v[124:127], v[18:33]
	v_cvt_pk_bf16_f32 v132, v50, v51
	v_cvt_pk_bf16_f32 v133, v54, v55
	v_cvt_pk_bf16_f32 v134, v52, v53
	v_cvt_pk_bf16_f32 v135, v56, v57
	s_nop 1
	s_waitcnt vmcnt(6)
	v_mfma_f32_32x32x16_bf16 v[2:17], v[214:217], v[132:135], v[2:17]
	s_waitcnt vmcnt(5)
	v_mfma_f32_32x32x16_bf16 v[18:33], v[184:187], v[132:135], v[18:33]
	v_cvt_pk_bf16_f32 v124, v76, v77
	v_cvt_pk_bf16_f32 v125, v96, v97
	v_cvt_pk_bf16_f32 v126, v40, v41
	v_cvt_pk_bf16_f32 v127, v46, v47
	s_nop 1
	s_waitcnt vmcnt(4)
	v_mfma_f32_32x32x16_bf16 v[2:17], v[230:233], v[124:127], v[2:17]
	s_waitcnt vmcnt(3)
	v_mfma_f32_32x32x16_bf16 v[18:33], v[192:195], v[124:127], v[18:33]
	v_cvt_pk_bf16_f32 v132, v64, v65
	v_cvt_pk_bf16_f32 v133, v72, v73
	v_cvt_pk_bf16_f32 v134, v66, v67
	v_cvt_pk_bf16_f32 v135, v74, v75
	s_nop 1
	s_waitcnt vmcnt(2)
	v_mfma_f32_32x32x16_bf16 v[2:17], v[226:229], v[132:135], v[2:17]
	v_mul_f32_e64 v44, v102, v156
	v_mul_f32_e64 v45, v103, v156
	s_waitcnt vmcnt(1)
	v_mfma_f32_32x32x16_bf16 v[18:33], v[140:143], v[132:135], v[18:33]
	v_cvt_pk_bf16_f32 v124, v112, v113
	v_cvt_pk_bf16_f32 v125, v70, v71
	v_cvt_pk_bf16_f32 v126, v44, v45
	v_cvt_pk_bf16_f32 v127, v68, v69
	s_waitcnt vmcnt(0)
	s_nop 0
	v_mfma_f32_32x32x16_bf16 v[2:17], v[210:213], v[124:127], v[2:17]
	v_mfma_f32_32x32x16_bf16 v[18:33], v[34:37], v[124:127], v[18:33]
	s_nop 10
	v_mul_f32_e32 v2, v0, v2
	v_mul_f32_e32 v3, v0, v3
	ds_write2st64_b32 v206, v2, v3 offset0:4 offset1:5
	v_mul_f32_e32 v18, v0, v18
	v_mul_f32_e32 v2, v0, v19
	ds_write2st64_b32 v206, v18, v2 offset0:20 offset1:21
	v_mul_f32_e32 v2, v0, v4
	v_mul_f32_e32 v4, v0, v5
	v_mul_f32_e32 v3, v0, v20
	ds_write2st64_b32 v206, v2, v4 offset0:6 offset1:7
	v_mul_f32_e32 v2, v0, v21
	ds_write2st64_b32 v206, v3, v2 offset0:22 offset1:23
	v_mul_f32_e32 v2, v0, v6
	v_mul_f32_e32 v4, v0, v7
	v_mul_f32_e32 v3, v0, v22
	ds_write2st64_b32 v206, v2, v4 offset0:8 offset1:9
	v_mul_f32_e32 v2, v0, v23
	ds_write2st64_b32 v206, v3, v2 offset0:24 offset1:25
	v_mul_f32_e32 v2, v0, v8
	v_mul_f32_e32 v4, v0, v9
	v_mul_f32_e32 v3, v0, v24
	ds_write2st64_b32 v206, v2, v4 offset0:10 offset1:11
	v_mul_f32_e32 v2, v0, v25
	ds_write2st64_b32 v206, v3, v2 offset0:26 offset1:27
	v_mul_f32_e32 v2, v0, v10
	v_mul_f32_e32 v4, v0, v11
	v_mul_f32_e32 v3, v0, v26
	ds_write2st64_b32 v206, v2, v4 offset0:12 offset1:13
	v_mul_f32_e32 v2, v0, v27
	ds_write2st64_b32 v206, v3, v2 offset0:28 offset1:29
	v_mul_f32_e32 v2, v0, v12
	v_mul_f32_e32 v4, v0, v13
	v_mul_f32_e32 v3, v0, v28
	ds_write2st64_b32 v206, v2, v4 offset0:14 offset1:15
	v_mul_f32_e32 v2, v0, v29
	ds_write2st64_b32 v206, v3, v2 offset0:30 offset1:31
	v_mul_f32_e32 v2, v0, v14
	v_mul_f32_e32 v4, v0, v15
	v_mul_f32_e32 v3, v0, v30
	ds_write2st64_b32 v206, v2, v4 offset0:16 offset1:17
	v_mul_f32_e32 v2, v0, v31
	ds_bpermute_b32 v20, v205, v123
	ds_write2st64_b32 v206, v3, v2 offset0:32 offset1:33
	v_mul_f32_e32 v2, v0, v16
	v_mul_f32_e32 v3, v0, v32
	v_mul_f32_e32 v4, v0, v17
	v_mul_f32_e32 v0, v0, v33
	ds_write2st64_b32 v206, v3, v0 offset0:34 offset1:35
	v_xor_b32_e32 v3, 1, v235
	v_cmp_lt_i32_e32 vcc, v3, v131
	ds_write2st64_b32 v206, v2, v4 offset0:18 offset1:19
	v_add_f32_e32 v4, v122, v123
	v_cndmask_b32_e32 v3, v235, v3, vcc
	v_add_f32_e32 v6, v120, v121
	v_cmp_gt_u32_e32 vcc, 32, v188
	v_add_f32_e32 v4, v6, v4
	v_lshlrev_b32_e32 v3, 2, v3
	s_waitcnt lgkmcnt(3)
	v_cndmask_b32_e64 v6, v20, 0, vcc
	v_add_f32_e32 v4, v6, v4
	s_nop 1
	v_mov_b32_dpp v6, v4 quad_perm:[1,0,3,2] row_mask:0xf bank_mask:0xf
	v_xor_b32_e32 v7, 2, v235
	v_cmp_lt_i32_e64 s[0:1], v7, v131
	ds_bpermute_b32 v19, v205, v117
	ds_bpermute_b32 v18, v205, v115
	v_cndmask_b32_e64 v7, v235, v7, s[0:1]
	v_lshlrev_b32_e32 v7, 2, v7
	s_waitcnt lgkmcnt(2)
	v_add_f32_e32 v21, v4, v6
	ds_bpermute_b32 v17, v205, v105
	ds_bpermute_b32 v16, v205, v61
	ds_bpermute_b32 v15, v205, v63
	ds_bpermute_b32 v14, v205, v99
	ds_bpermute_b32 v13, v205, v49
	ds_bpermute_b32 v12, v205, v55
	ds_bpermute_b32 v11, v205, v57
	ds_bpermute_b32 v10, v205, v97
	ds_bpermute_b32 v9, v205, v47
	ds_bpermute_b32 v8, v205, v73
	ds_bpermute_b32 v5, v205, v75
	ds_bpermute_b32 v0, v205, v71
	ds_bpermute_b32 v2, v205, v69
	s_nop 1
	v_mov_b32_dpp v22, v21 quad_perm:[2,3,0,1] row_mask:0xf bank_mask:0xf
	v_lshlrev_b32_e32 v4, 5, v129
	v_add_u32_e32 v6, v4, v196
	v_lshl_add_u32 v6, v6, 2, s83
	s_and_saveexec_b64 s[0:1], s[8:9]
	s_cbranch_execz .LBB0_1568
	s_waitcnt lgkmcnt(0)
	v_add_f32_e32 v21, v21, v22
	ds_write_b32 v6, v21
